# GLU prologue: the eight serialized staging loads (load, wait, ds_write) issued together with the k-loop weight loads before the first wait
# speedup vs baseline: 1.0242x; 1.0065x over previous
; template <int NT2>
; DI void glu_prologue(const Params& p, char* lds, int l, int tile0, int tile1) {
;     ...
;     __syncthreads();
; #pragma unroll
;     for (int tt = 0; tt < NT2; ++tt) {
;         const int tile = tt ? tile1 : tile0;
;         char* Ys = lds + tt * 33792;
;         const bf16_t* ysg = WS_PTR(const bf16_t, OFF_YS) + (size_t)tile * 64 * 256;
; #pragma unroll
;         for (int i = 0; i < 4; ++i) {
;             const int idx = tid + NTHR * i, row = idx >> 5, c16 = idx & 31;
;             *(u32x4*)(Ys + row * 528 + c16 * 16) = *(const u32x4*)(ysg + (size_t)row * 256 + c16 * 8);
;         }
;     }
;     __syncthreads();
;     f32x4 acc[NT2][4][2];
; #pragma unroll
;     for (int tt = 0; tt < NT2; ++tt)
; #pragma unroll
;         for (int mt = 0; mt < 4; ++mt) { acc[tt][mt][0] = (f32x4){0.f, 0.f, 0.f, 0.f}; acc[tt][mt][1] = (f32x4){0.f, 0.f, 0.f, 0.f}; }
;     const bf16_t* Wg = WS_PTR(const bf16_t, OFF_WGLU) + (size_t)l * 65536;
; #pragma unroll 2
;     for (int ks = 0; ks < 8; ++ks) {
;         bf16x8 bb[2];
; #pragma unroll
;         for (int nt = 0; nt < 2; ++nt) bb[nt] = *(const bf16x8*)(Wg + (wid * 32 + nt * 16 + l15) * 256 + 32 * ks + 8 * quad);
.LBB0_90:
	s_and_b64 vcc, exec, s[6:7]
	s_cbranch_vccz .LBB0_94
	s_ashr_i32 s35, s34, 31
	v_mov_b32_e32 v78, v212
	s_lshl_b64 s[8:9], s[34:35], 15
	v_readlane_b32 s40, v244, 46
	s_add_u32 s6, s40, s8
	v_lshlrev_b32_e32 v0, 4, v78
	v_ashrrev_i32_e32 v8, 5, v78
	v_readlane_b32 s47, v244, 47
	v_and_b32_e32 v0, 0x1f0, v0
	v_ashrrev_i32_e32 v9, 31, v8
	s_addc_u32 s7, s47, s9
	v_lshlrev_b64 v[10:11], 9, v[8:9]
	v_lshl_add_u64 v[12:13], s[6:7], 0, v[0:1]
	v_lshl_add_u64 v[2:3], v[12:13], 0, v[10:11]
	s_barrier
	global_load_dwordx4 v[172:175], v[2:3], off
	v_add_u32_e32 v6, 0, v0
	s_movk_i32 s46, 0x210
	v_mad_u64_u32 v[8:9], s[6:7], v8, s46, v[6:7]
	s_ashr_i32 s49, s48, 31
	v_and_b32_e32 v84, 15, v78
	v_ashrrev_i32_e32 v76, 6, v78
	v_bfe_u32 v79, v78, 4, 2
	v_mul_u32_u24_e32 v82, 0x210, v84
	v_add_u32_e32 v2, 0x200, v78
	v_ashrrev_i32_e32 v14, 5, v2
	v_ashrrev_i32_e32 v15, 31, v14
	v_lshlrev_b64 v[16:17], 9, v[14:15]
	v_lshl_add_u64 v[2:3], v[12:13], 0, v[16:17]
	global_load_dwordx4 v[176:179], v[2:3], off
	v_mad_u64_u32 v[14:15], s[6:7], v14, s46, v[6:7]
	v_add_u32_e32 v2, 0x400, v78
	v_ashrrev_i32_e32 v18, 5, v2
	v_ashrrev_i32_e32 v19, 31, v18
	v_lshlrev_b64 v[20:21], 9, v[18:19]
	v_lshl_add_u64 v[2:3], v[12:13], 0, v[20:21]
	global_load_dwordx4 v[180:183], v[2:3], off
	v_mad_u64_u32 v[18:19], s[6:7], v18, s46, v[6:7]
	v_add_u32_e32 v2, 0x600, v78
	v_ashrrev_i32_e32 v22, 5, v2
	v_ashrrev_i32_e32 v23, 31, v22
	v_lshlrev_b64 v[24:25], 9, v[22:23]
	v_lshl_add_u64 v[2:3], v[12:13], 0, v[24:25]
	global_load_dwordx4 v[184:187], v[2:3], off
	v_mad_u64_u32 v[6:7], s[6:7], v22, s46, v[6:7]
	s_lshl_b64 s[6:7], s[48:49], 15
	s_add_u32 s46, s40, s6
	s_addc_u32 s47, s47, s7
	v_lshl_add_u64 v[12:13], s[46:47], 0, v[0:1]
	v_lshlrev_b32_e32 v0, 8, v84
	s_mov_b64 s[46:47], 0
	v_lshl_add_u64 v[2:3], v[12:13], 0, v[10:11]
	global_load_dwordx4 v[188:191], v[2:3], off
	v_lshl_add_u64 v[2:3], v[12:13], 0, v[16:17]
	global_load_dwordx4 v[192:195], v[2:3], off
	v_lshl_add_u64 v[2:3], v[12:13], 0, v[20:21]
	global_load_dwordx4 v[196:199], v[2:3], off
	v_lshl_add_u64 v[2:3], v[12:13], 0, v[24:25]
	global_load_dwordx4 v[200:203], v[2:3], off
	v_lshl_or_b32 v2, v76, 13, v0
	v_ashrrev_i32_e32 v3, 31, v2
	v_lshlrev_b32_e32 v4, 4, v79
	v_lshlrev_b64 v[2:3], 1, v[2:3]
	v_or_b32_e32 v2, v2, v4
	v_lshl_add_u64 v[66:67], s[30:31], 0, v[2:3]
	v_add_co_u32_e32 v80, vcc, s87, v66
	s_nop 1
	v_addc_co_u32_e32 v81, vcc, 0, v67, vcc
	v_add_co_u32_e32 v102, vcc, s86, v66
	s_nop 1
	v_addc_co_u32_e32 v103, vcc, 0, v67, vcc
	global_load_dwordx4 v[104:107], v[80:81], off
	global_load_dwordx4 v[108:111], v[102:103], off
	global_load_dwordx4 v[112:115], v[80:81], off offset:64
	global_load_dwordx4 v[116:119], v[102:103], off offset:64
	global_load_dwordx4 v[120:123], v[80:81], off offset:128
	global_load_dwordx4 v[124:127], v[102:103], off offset:128
	global_load_dwordx4 v[128:131], v[80:81], off offset:192
	global_load_dwordx4 v[132:135], v[102:103], off offset:192
	global_load_dwordx4 v[140:143], v[80:81], off offset:256
	global_load_dwordx4 v[144:147], v[102:103], off offset:256
	global_load_dwordx4 v[148:151], v[80:81], off offset:320
	global_load_dwordx4 v[152:155], v[102:103], off offset:320
	global_load_dwordx4 v[156:159], v[80:81], off offset:384
	global_load_dwordx4 v[160:163], v[102:103], off offset:384
	global_load_dwordx4 v[164:167], v[80:81], off offset:448
	global_load_dwordx4 v[168:171], v[102:103], off offset:448
	s_waitcnt vmcnt(23)
	ds_write_b128 v8, v[172:175]
	s_waitcnt vmcnt(22)
	ds_write_b128 v14, v[176:179]
	s_waitcnt vmcnt(21)
	ds_write_b128 v18, v[180:183]
	s_waitcnt vmcnt(20)
	ds_write_b128 v6, v[184:187]
	s_waitcnt vmcnt(19)
	ds_write_b128 v8, v[188:191] offset:33792
	s_waitcnt vmcnt(18)
	ds_write_b128 v14, v[192:195] offset:33792
	s_waitcnt vmcnt(17)
	ds_write_b128 v18, v[196:199] offset:33792
	s_waitcnt vmcnt(16)
	ds_write_b128 v6, v[200:203] offset:33792
	v_mov_b32_e32 v2, 0
	v_add3_u32 v77, v82, v4, 0
	v_mov_b32_e32 v3, v2
	v_mov_b32_e32 v4, v2
	v_mov_b32_e32 v5, v2
	v_mov_b32_e32 v14, v2
	v_mov_b32_e32 v15, v2
	v_mov_b32_e32 v16, v2
	v_mov_b32_e32 v17, v2
	v_mov_b32_e32 v18, v2
	v_mov_b32_e32 v19, v2
	v_mov_b32_e32 v20, v2
	v_mov_b32_e32 v21, v2
	v_mov_b32_e32 v22, v2
	v_mov_b32_e32 v23, v2
	v_mov_b32_e32 v24, v2
	v_mov_b32_e32 v25, v2
	v_mov_b32_e32 v26, v2
	v_mov_b32_e32 v27, v2
	v_mov_b32_e32 v28, v2
	v_mov_b32_e32 v29, v2
	v_mov_b32_e32 v34, v2
	v_mov_b32_e32 v35, v2
	v_mov_b32_e32 v36, v2
	v_mov_b32_e32 v37, v2
	v_mov_b32_e32 v30, v2
	v_mov_b32_e32 v31, v2
	v_mov_b32_e32 v32, v2
	v_mov_b32_e32 v33, v2
	v_mov_b32_e32 v38, v2
	v_mov_b32_e32 v39, v2
	v_mov_b32_e32 v40, v2
	v_mov_b32_e32 v41, v2
	v_mov_b32_e32 v42, v2
	v_mov_b32_e32 v43, v2
	v_mov_b32_e32 v44, v2
	v_mov_b32_e32 v45, v2
	v_mov_b32_e32 v46, v2
	v_mov_b32_e32 v47, v2
	v_mov_b32_e32 v48, v2
	v_mov_b32_e32 v49, v2
	v_mov_b32_e32 v50, v2
	v_mov_b32_e32 v51, v2
	v_mov_b32_e32 v52, v2
	v_mov_b32_e32 v53, v2
	v_mov_b32_e32 v68, v2
	v_mov_b32_e32 v69, v2
	v_mov_b32_e32 v70, v2
	v_mov_b32_e32 v71, v2
	v_mov_b32_e32 v58, v2
	v_mov_b32_e32 v59, v2
	v_mov_b32_e32 v60, v2
	v_mov_b32_e32 v61, v2
	v_mov_b32_e32 v54, v2
	v_mov_b32_e32 v55, v2
	v_mov_b32_e32 v56, v2
	v_mov_b32_e32 v57, v2
	v_mov_b32_e32 v10, v2
	v_mov_b32_e32 v11, v2
	v_mov_b32_e32 v12, v2
	v_mov_b32_e32 v13, v2
	v_mov_b32_e32 v6, v2
	v_mov_b32_e32 v7, v2
	v_mov_b32_e32 v8, v2
	v_mov_b32_e32 v9, v2
	s_waitcnt lgkmcnt(0)
	s_barrier
; DI f32x4 mfma16(bf16x8 a, bf16x8 b, f32x4 c) { return __builtin_amdgcn_mfma_f32_16x16x32_bf16(a, b, c, 0, 0, 0); }
; template <int NT2>
; DI void glu_prologue(const Params& p, char* lds, int l, int tile0, int tile1) {
;     ...
;     for (int ks = 0; ks < 8; ++ks) {
;         bf16x8 bb[2];
; #pragma unroll
;         for (int nt = 0; nt < 2; ++nt) bb[nt] = *(const bf16x8*)(Wg + (wid * 32 + nt * 16 + l15) * 256 + 32 * ks + 8 * quad);
; #pragma unroll
;         for (int tt = 0; tt < NT2; ++tt) {
;             const char* Ys = lds + tt * 33792;
;             bf16x8 a[4];
; #pragma unroll
;             for (int mt = 0; mt < 4; ++mt) a[mt] = *(const bf16x8*)(Ys + (mt * 16 + l15) * 528 + (32 * ks + 8 * quad) * 2);
; #pragma unroll
;             for (int mt = 0; mt < 4; ++mt)
; #pragma unroll
;                 for (int nt = 0; nt < 2; ++nt) acc[tt][mt][nt] = mfma16(bb[nt], a[mt], acc[tt][mt][nt]);
;         }
	s_waitcnt vmcnt(14)
	ds_read_b128 v[86:89], v77
	ds_read_b128 v[90:93], v77 offset:8448
	ds_read_b128 v[94:97], v77 offset:16896
	ds_read_b128 v[98:101], v77 offset:25344
	s_waitcnt lgkmcnt(3)
	v_mfma_f32_16x16x32_bf16 v[54:57], v[104:107], v[86:89], v[54:57]
	v_mfma_f32_16x16x32_bf16 v[58:61], v[108:111], v[86:89], v[58:61]
	s_waitcnt lgkmcnt(2)
	v_mfma_f32_16x16x32_bf16 v[68:71], v[104:107], v[90:93], v[68:71]
	v_mfma_f32_16x16x32_bf16 v[50:53], v[108:111], v[90:93], v[50:53]
	s_waitcnt lgkmcnt(1)
	v_mfma_f32_16x16x32_bf16 v[46:49], v[104:107], v[94:97], v[46:49]
	v_mfma_f32_16x16x32_bf16 v[42:45], v[108:111], v[94:97], v[42:45]
	s_waitcnt lgkmcnt(0)
	v_mfma_f32_16x16x32_bf16 v[38:41], v[104:107], v[98:101], v[38:41]
	v_mfma_f32_16x16x32_bf16 v[30:33], v[108:111], v[98:101], v[30:33]
	ds_read_b128 v[86:89], v77 offset:33792
	ds_read_b128 v[90:93], v77 offset:42240
	ds_read_b128 v[94:97], v77 offset:50688
	ds_read_b128 v[98:101], v77 offset:59136
	s_waitcnt lgkmcnt(3)
	v_mfma_f32_16x16x32_bf16 v[34:37], v[104:107], v[86:89], v[34:37]
	v_mfma_f32_16x16x32_bf16 v[26:29], v[108:111], v[86:89], v[26:29]
	s_waitcnt lgkmcnt(2)
	v_mfma_f32_16x16x32_bf16 v[22:25], v[104:107], v[90:93], v[22:25]
	v_mfma_f32_16x16x32_bf16 v[18:21], v[108:111], v[90:93], v[18:21]
	s_waitcnt lgkmcnt(1)
	v_mfma_f32_16x16x32_bf16 v[14:17], v[104:107], v[94:97], v[14:17]
	v_mfma_f32_16x16x32_bf16 v[2:5], v[108:111], v[94:97], v[2:5]
	s_waitcnt lgkmcnt(0)
	v_mfma_f32_16x16x32_bf16 v[10:13], v[104:107], v[98:101], v[10:13]
	v_mfma_f32_16x16x32_bf16 v[6:9], v[108:111], v[98:101], v[6:9]
	s_waitcnt vmcnt(12)
	ds_read_b128 v[86:89], v77 offset:64
	ds_read_b128 v[90:93], v77 offset:8512
	ds_read_b128 v[94:97], v77 offset:16960
	ds_read_b128 v[98:101], v77 offset:25408
	s_waitcnt lgkmcnt(3)
	v_mfma_f32_16x16x32_bf16 v[54:57], v[112:115], v[86:89], v[54:57]
	v_mfma_f32_16x16x32_bf16 v[58:61], v[116:119], v[86:89], v[58:61]
	s_waitcnt lgkmcnt(2)
	v_mfma_f32_16x16x32_bf16 v[68:71], v[112:115], v[90:93], v[68:71]
	v_mfma_f32_16x16x32_bf16 v[50:53], v[116:119], v[90:93], v[50:53]
	s_waitcnt lgkmcnt(1)
	v_mfma_f32_16x16x32_bf16 v[46:49], v[112:115], v[94:97], v[46:49]
	v_mfma_f32_16x16x32_bf16 v[42:45], v[116:119], v[94:97], v[42:45]
	s_waitcnt lgkmcnt(0)
	v_mfma_f32_16x16x32_bf16 v[38:41], v[112:115], v[98:101], v[38:41]
	v_mfma_f32_16x16x32_bf16 v[30:33], v[116:119], v[98:101], v[30:33]
	ds_read_b128 v[86:89], v77 offset:33856
	ds_read_b128 v[90:93], v77 offset:42304
	ds_read_b128 v[94:97], v77 offset:50752
	ds_read_b128 v[98:101], v77 offset:59200
	s_waitcnt lgkmcnt(3)
	v_mfma_f32_16x16x32_bf16 v[34:37], v[112:115], v[86:89], v[34:37]
	v_mfma_f32_16x16x32_bf16 v[26:29], v[116:119], v[86:89], v[26:29]
	s_waitcnt lgkmcnt(2)
	v_mfma_f32_16x16x32_bf16 v[22:25], v[112:115], v[90:93], v[22:25]
	v_mfma_f32_16x16x32_bf16 v[18:21], v[116:119], v[90:93], v[18:21]
	s_waitcnt lgkmcnt(1)
	v_mfma_f32_16x16x32_bf16 v[14:17], v[112:115], v[94:97], v[14:17]
	v_mfma_f32_16x16x32_bf16 v[2:5], v[116:119], v[94:97], v[2:5]
	s_waitcnt lgkmcnt(0)
	v_mfma_f32_16x16x32_bf16 v[10:13], v[112:115], v[98:101], v[10:13]
	v_mfma_f32_16x16x32_bf16 v[6:9], v[116:119], v[98:101], v[6:9]
	s_waitcnt vmcnt(10)
	ds_read_b128 v[86:89], v77 offset:128
	ds_read_b128 v[90:93], v77 offset:8576
	ds_read_b128 v[94:97], v77 offset:17024
	ds_read_b128 v[98:101], v77 offset:25472
	s_waitcnt lgkmcnt(3)
	v_mfma_f32_16x16x32_bf16 v[54:57], v[120:123], v[86:89], v[54:57]
	v_mfma_f32_16x16x32_bf16 v[58:61], v[124:127], v[86:89], v[58:61]
	s_waitcnt lgkmcnt(2)
	v_mfma_f32_16x16x32_bf16 v[68:71], v[120:123], v[90:93], v[68:71]
	v_mfma_f32_16x16x32_bf16 v[50:53], v[124:127], v[90:93], v[50:53]
	s_waitcnt lgkmcnt(1)
	v_mfma_f32_16x16x32_bf16 v[46:49], v[120:123], v[94:97], v[46:49]
	v_mfma_f32_16x16x32_bf16 v[42:45], v[124:127], v[94:97], v[42:45]
	s_waitcnt lgkmcnt(0)
	v_mfma_f32_16x16x32_bf16 v[38:41], v[120:123], v[98:101], v[38:41]
	v_mfma_f32_16x16x32_bf16 v[30:33], v[124:127], v[98:101], v[30:33]
	ds_read_b128 v[86:89], v77 offset:33920
	ds_read_b128 v[90:93], v77 offset:42368
	ds_read_b128 v[94:97], v77 offset:50816
	ds_read_b128 v[98:101], v77 offset:59264
	s_waitcnt lgkmcnt(3)
	v_mfma_f32_16x16x32_bf16 v[34:37], v[120:123], v[86:89], v[34:37]
	v_mfma_f32_16x16x32_bf16 v[26:29], v[124:127], v[86:89], v[26:29]
	s_waitcnt lgkmcnt(2)
	v_mfma_f32_16x16x32_bf16 v[22:25], v[120:123], v[90:93], v[22:25]
	v_mfma_f32_16x16x32_bf16 v[18:21], v[124:127], v[90:93], v[18:21]
	s_waitcnt lgkmcnt(1)
	v_mfma_f32_16x16x32_bf16 v[14:17], v[120:123], v[94:97], v[14:17]
	v_mfma_f32_16x16x32_bf16 v[2:5], v[124:127], v[94:97], v[2:5]
	s_waitcnt lgkmcnt(0)
	v_mfma_f32_16x16x32_bf16 v[10:13], v[120:123], v[98:101], v[10:13]
	v_mfma_f32_16x16x32_bf16 v[6:9], v[124:127], v[98:101], v[6:9]
	s_waitcnt vmcnt(8)
	ds_read_b128 v[86:89], v77 offset:192
	ds_read_b128 v[90:93], v77 offset:8640
	ds_read_b128 v[94:97], v77 offset:17088
	ds_read_b128 v[98:101], v77 offset:25536
	s_waitcnt lgkmcnt(3)
	v_mfma_f32_16x16x32_bf16 v[54:57], v[128:131], v[86:89], v[54:57]
	v_mfma_f32_16x16x32_bf16 v[58:61], v[132:135], v[86:89], v[58:61]
	s_waitcnt lgkmcnt(2)
	v_mfma_f32_16x16x32_bf16 v[68:71], v[128:131], v[90:93], v[68:71]
	v_mfma_f32_16x16x32_bf16 v[50:53], v[132:135], v[90:93], v[50:53]
	s_waitcnt lgkmcnt(1)
	v_mfma_f32_16x16x32_bf16 v[46:49], v[128:131], v[94:97], v[46:49]
	v_mfma_f32_16x16x32_bf16 v[42:45], v[132:135], v[94:97], v[42:45]
	s_waitcnt lgkmcnt(0)
	v_mfma_f32_16x16x32_bf16 v[38:41], v[128:131], v[98:101], v[38:41]
	v_mfma_f32_16x16x32_bf16 v[30:33], v[132:135], v[98:101], v[30:33]
	ds_read_b128 v[86:89], v77 offset:33984
	ds_read_b128 v[90:93], v77 offset:42432
	ds_read_b128 v[94:97], v77 offset:50880
	ds_read_b128 v[98:101], v77 offset:59328
	s_waitcnt lgkmcnt(3)
; DI f32x4 mfma16(bf16x8 a, bf16x8 b, f32x4 c) { return __builtin_amdgcn_mfma_f32_16x16x32_bf16(a, b, c, 0, 0, 0); }
; template <int NT2>
; DI void glu_prologue(const Params& p, char* lds, int l, int tile0, int tile1) {
;     ...
;     for (int ks = 0; ks < 8; ++ks) {
;         bf16x8 bb[2];
; #pragma unroll
;         for (int nt = 0; nt < 2; ++nt) bb[nt] = *(const bf16x8*)(Wg + (wid * 32 + nt * 16 + l15) * 256 + 32 * ks + 8 * quad);
; #pragma unroll
;         for (int tt = 0; tt < NT2; ++tt) {
;             const char* Ys = lds + tt * 33792;
;             bf16x8 a[4];
; #pragma unroll
;             for (int mt = 0; mt < 4; ++mt) a[mt] = *(const bf16x8*)(Ys + (mt * 16 + l15) * 528 + (32 * ks + 8 * quad) * 2);
; #pragma unroll
;             for (int mt = 0; mt < 4; ++mt)
; #pragma unroll
;                 for (int nt = 0; nt < 2; ++nt) acc[tt][mt][nt] = mfma16(bb[nt], a[mt], acc[tt][mt][nt]);
;         }
	v_mfma_f32_16x16x32_bf16 v[34:37], v[128:131], v[86:89], v[34:37]
	v_mfma_f32_16x16x32_bf16 v[26:29], v[132:135], v[86:89], v[26:29]
	s_waitcnt lgkmcnt(2)
	v_mfma_f32_16x16x32_bf16 v[22:25], v[128:131], v[90:93], v[22:25]
	v_mfma_f32_16x16x32_bf16 v[18:21], v[132:135], v[90:93], v[18:21]
	s_waitcnt lgkmcnt(1)
	v_mfma_f32_16x16x32_bf16 v[14:17], v[128:131], v[94:97], v[14:17]
	v_mfma_f32_16x16x32_bf16 v[2:5], v[132:135], v[94:97], v[2:5]
	s_waitcnt lgkmcnt(0)
	v_mfma_f32_16x16x32_bf16 v[10:13], v[128:131], v[98:101], v[10:13]
	v_mfma_f32_16x16x32_bf16 v[6:9], v[132:135], v[98:101], v[6:9]
	s_waitcnt vmcnt(6)
	ds_read_b128 v[86:89], v77 offset:256
	ds_read_b128 v[90:93], v77 offset:8704
	ds_read_b128 v[94:97], v77 offset:17152
	ds_read_b128 v[98:101], v77 offset:25600
	s_waitcnt lgkmcnt(3)
	v_mfma_f32_16x16x32_bf16 v[54:57], v[140:143], v[86:89], v[54:57]
	v_mfma_f32_16x16x32_bf16 v[58:61], v[144:147], v[86:89], v[58:61]
	s_waitcnt lgkmcnt(2)
	v_mfma_f32_16x16x32_bf16 v[68:71], v[140:143], v[90:93], v[68:71]
	v_mfma_f32_16x16x32_bf16 v[50:53], v[144:147], v[90:93], v[50:53]
	s_waitcnt lgkmcnt(1)
	v_mfma_f32_16x16x32_bf16 v[46:49], v[140:143], v[94:97], v[46:49]
	v_mfma_f32_16x16x32_bf16 v[42:45], v[144:147], v[94:97], v[42:45]
	s_waitcnt lgkmcnt(0)
	v_mfma_f32_16x16x32_bf16 v[38:41], v[140:143], v[98:101], v[38:41]
	v_mfma_f32_16x16x32_bf16 v[30:33], v[144:147], v[98:101], v[30:33]
	ds_read_b128 v[86:89], v77 offset:34048
	ds_read_b128 v[90:93], v77 offset:42496
	ds_read_b128 v[94:97], v77 offset:50944
	ds_read_b128 v[98:101], v77 offset:59392
	s_waitcnt lgkmcnt(3)
	v_mfma_f32_16x16x32_bf16 v[34:37], v[140:143], v[86:89], v[34:37]
	v_mfma_f32_16x16x32_bf16 v[26:29], v[144:147], v[86:89], v[26:29]
	s_waitcnt lgkmcnt(2)
	v_mfma_f32_16x16x32_bf16 v[22:25], v[140:143], v[90:93], v[22:25]
	v_mfma_f32_16x16x32_bf16 v[18:21], v[144:147], v[90:93], v[18:21]
	s_waitcnt lgkmcnt(1)
	v_mfma_f32_16x16x32_bf16 v[14:17], v[140:143], v[94:97], v[14:17]
	v_mfma_f32_16x16x32_bf16 v[2:5], v[144:147], v[94:97], v[2:5]
	s_waitcnt lgkmcnt(0)
	v_mfma_f32_16x16x32_bf16 v[10:13], v[140:143], v[98:101], v[10:13]
	v_mfma_f32_16x16x32_bf16 v[6:9], v[144:147], v[98:101], v[6:9]
	s_waitcnt vmcnt(4)
	ds_read_b128 v[86:89], v77 offset:320
	ds_read_b128 v[90:93], v77 offset:8768
	ds_read_b128 v[94:97], v77 offset:17216
	ds_read_b128 v[98:101], v77 offset:25664
	s_waitcnt lgkmcnt(3)
	v_mfma_f32_16x16x32_bf16 v[54:57], v[148:151], v[86:89], v[54:57]
	v_mfma_f32_16x16x32_bf16 v[58:61], v[152:155], v[86:89], v[58:61]
	s_waitcnt lgkmcnt(2)
	v_mfma_f32_16x16x32_bf16 v[68:71], v[148:151], v[90:93], v[68:71]
	v_mfma_f32_16x16x32_bf16 v[50:53], v[152:155], v[90:93], v[50:53]
	s_waitcnt lgkmcnt(1)
	v_mfma_f32_16x16x32_bf16 v[46:49], v[148:151], v[94:97], v[46:49]
	v_mfma_f32_16x16x32_bf16 v[42:45], v[152:155], v[94:97], v[42:45]
	s_waitcnt lgkmcnt(0)
	v_mfma_f32_16x16x32_bf16 v[38:41], v[148:151], v[98:101], v[38:41]
	v_mfma_f32_16x16x32_bf16 v[30:33], v[152:155], v[98:101], v[30:33]
	ds_read_b128 v[86:89], v77 offset:34112
	ds_read_b128 v[90:93], v77 offset:42560
	ds_read_b128 v[94:97], v77 offset:51008
	ds_read_b128 v[98:101], v77 offset:59456
	s_waitcnt lgkmcnt(3)
	v_mfma_f32_16x16x32_bf16 v[34:37], v[148:151], v[86:89], v[34:37]
	v_mfma_f32_16x16x32_bf16 v[26:29], v[152:155], v[86:89], v[26:29]
	s_waitcnt lgkmcnt(2)
	v_mfma_f32_16x16x32_bf16 v[22:25], v[148:151], v[90:93], v[22:25]
	v_mfma_f32_16x16x32_bf16 v[18:21], v[152:155], v[90:93], v[18:21]
	s_waitcnt lgkmcnt(1)
	v_mfma_f32_16x16x32_bf16 v[14:17], v[148:151], v[94:97], v[14:17]
	v_mfma_f32_16x16x32_bf16 v[2:5], v[152:155], v[94:97], v[2:5]
	s_waitcnt lgkmcnt(0)
	v_mfma_f32_16x16x32_bf16 v[10:13], v[148:151], v[98:101], v[10:13]
	v_mfma_f32_16x16x32_bf16 v[6:9], v[152:155], v[98:101], v[6:9]
	s_waitcnt vmcnt(2)
	ds_read_b128 v[86:89], v77 offset:384
	ds_read_b128 v[90:93], v77 offset:8832
	ds_read_b128 v[94:97], v77 offset:17280
	ds_read_b128 v[98:101], v77 offset:25728
	s_waitcnt lgkmcnt(3)
	v_mfma_f32_16x16x32_bf16 v[54:57], v[156:159], v[86:89], v[54:57]
	v_mfma_f32_16x16x32_bf16 v[58:61], v[160:163], v[86:89], v[58:61]
	s_waitcnt lgkmcnt(2)
	v_mfma_f32_16x16x32_bf16 v[68:71], v[156:159], v[90:93], v[68:71]
	v_mfma_f32_16x16x32_bf16 v[50:53], v[160:163], v[90:93], v[50:53]
	s_waitcnt lgkmcnt(1)
	v_mfma_f32_16x16x32_bf16 v[46:49], v[156:159], v[94:97], v[46:49]
	v_mfma_f32_16x16x32_bf16 v[42:45], v[160:163], v[94:97], v[42:45]
	s_waitcnt lgkmcnt(0)
	v_mfma_f32_16x16x32_bf16 v[38:41], v[156:159], v[98:101], v[38:41]
	v_mfma_f32_16x16x32_bf16 v[30:33], v[160:163], v[98:101], v[30:33]
	ds_read_b128 v[86:89], v77 offset:34176
	ds_read_b128 v[90:93], v77 offset:42624
	ds_read_b128 v[94:97], v77 offset:51072
	ds_read_b128 v[98:101], v77 offset:59520
	s_waitcnt lgkmcnt(3)
	v_mfma_f32_16x16x32_bf16 v[34:37], v[156:159], v[86:89], v[34:37]
	v_mfma_f32_16x16x32_bf16 v[26:29], v[160:163], v[86:89], v[26:29]
	s_waitcnt lgkmcnt(2)
	v_mfma_f32_16x16x32_bf16 v[22:25], v[156:159], v[90:93], v[22:25]
	v_mfma_f32_16x16x32_bf16 v[18:21], v[160:163], v[90:93], v[18:21]
	s_waitcnt lgkmcnt(1)
	v_mfma_f32_16x16x32_bf16 v[14:17], v[156:159], v[94:97], v[14:17]
	v_mfma_f32_16x16x32_bf16 v[2:5], v[160:163], v[94:97], v[2:5]
	s_waitcnt lgkmcnt(0)
	v_mfma_f32_16x16x32_bf16 v[10:13], v[156:159], v[98:101], v[10:13]
	v_mfma_f32_16x16x32_bf16 v[6:9], v[160:163], v[98:101], v[6:9]
	s_waitcnt vmcnt(0)
	ds_read_b128 v[86:89], v77 offset:448
	ds_read_b128 v[90:93], v77 offset:8896
	ds_read_b128 v[94:97], v77 offset:17344
	ds_read_b128 v[98:101], v77 offset:25792
	s_waitcnt lgkmcnt(3)
; DI unsigned pk2(float lo, float hi) { const f32x2 v = {lo, hi}; const bf16x2_t b = __builtin_convertvector(v, bf16x2_t); return __builtin_bit_cast(unsigned, b); }
; DI float bf2f(unsigned b) { return __uint_as_float(b << 16); }
; DI float sigmoid_f(float x) { return __builtin_amdgcn_rcpf(1.f + __builtin_amdgcn_exp2f(x * -1.44269504089f)); }
; DI f32x4 mfma16(bf16x8 a, bf16x8 b, f32x4 c) { return __builtin_amdgcn_mfma_f32_16x16x32_bf16(a, b, c, 0, 0, 0); }
; DI size_t y_off(int tok, int col) { return ((size_t)(((tok >> 6) * 32 + (col >> 5)) * 64 + (tok & 63))) * 32 + (col & 31); }
; template <int NT2>
; DI void glu_prologue(const Params& p, char* lds, int l, int tile0, int tile1) {
;     ...
;             for (int mt = 0; mt < 4; ++mt)
; #pragma unroll
;                 for (int nt = 0; nt < 2; ++nt) acc[tt][mt][nt] = mfma16(bb[nt], a[mt], acc[tt][mt][nt]);
;         }
;     }
;     bf16_t* yo = WS_PTR(bf16_t, OFF_Y);
; #pragma unroll
;     for (int tt = 0; tt < NT2; ++tt) {
;         const int tile = tt ? tile1 : tile0;
;         const char* Ys = lds + tt * 33792;
;         const bf16_t* sg = WS_PTR(const bf16_t, OFF_SG) + (size_t)tile * 64 * 256;
; #pragma unroll
;         for (int mt = 0; mt < 4; ++mt) {
;             const int tok = mt * 16 + l15;
; #pragma unroll
;             for (int nt = 0; nt < 2; ++nt) {
;                 const int n0 = wid * 32 + nt * 16 + quad * 4;
;                 const f32x4 gb = *(const f32x4*)(p.glu_b + l * 256 + n0);
;                 const u32x2 yv = *(const u32x2*)(Ys + tok * 528 + n0 * 2);
;                 const u32x2 sv = *(const u32x2*)(sg + (size_t)tok * 256 + n0);
;                 float o[4];
;                 o[0] = sigmoid_f(acc[tt][mt][nt][0] + gb[0]) * bf2f(yv[0] & 0xffffu) * bf2f(sv[0] & 0xffffu);
;                 o[1] = sigmoid_f(acc[tt][mt][nt][1] + gb[1]) * bf2f(yv[0] >> 16) * bf2f(sv[0] >> 16);
;                 o[2] = sigmoid_f(acc[tt][mt][nt][2] + gb[2]) * bf2f(yv[1] & 0xffffu) * bf2f(sv[1] & 0xffffu);
;                 o[3] = sigmoid_f(acc[tt][mt][nt][3] + gb[3]) * bf2f(yv[1] >> 16) * bf2f(sv[1] >> 16);
;                 *(u32x2*)(yo + y_off(tile * 64 + tok, 512 + n0)) = (u32x2){pk2(o[0], o[1]), pk2(o[2], o[3])};
;             }
	v_mfma_f32_16x16x32_bf16 v[54:57], v[164:167], v[86:89], v[54:57]
	v_mfma_f32_16x16x32_bf16 v[58:61], v[168:171], v[86:89], v[58:61]
	s_waitcnt lgkmcnt(2)
	v_mfma_f32_16x16x32_bf16 v[68:71], v[164:167], v[90:93], v[68:71]
	v_mfma_f32_16x16x32_bf16 v[50:53], v[168:171], v[90:93], v[50:53]
	s_waitcnt lgkmcnt(1)
	v_mfma_f32_16x16x32_bf16 v[46:49], v[164:167], v[94:97], v[46:49]
	v_mfma_f32_16x16x32_bf16 v[42:45], v[168:171], v[94:97], v[42:45]
	s_waitcnt lgkmcnt(0)
	v_mfma_f32_16x16x32_bf16 v[38:41], v[164:167], v[98:101], v[38:41]
	v_mfma_f32_16x16x32_bf16 v[30:33], v[168:171], v[98:101], v[30:33]
	ds_read_b128 v[86:89], v77 offset:34240
	ds_read_b128 v[90:93], v77 offset:42688
	ds_read_b128 v[94:97], v77 offset:51136
	ds_read_b128 v[98:101], v77 offset:59584
	s_waitcnt lgkmcnt(3)
	v_mfma_f32_16x16x32_bf16 v[34:37], v[164:167], v[86:89], v[34:37]
	v_mfma_f32_16x16x32_bf16 v[26:29], v[168:171], v[86:89], v[26:29]
	s_waitcnt lgkmcnt(2)
	v_mfma_f32_16x16x32_bf16 v[22:25], v[164:167], v[90:93], v[22:25]
	v_mfma_f32_16x16x32_bf16 v[18:21], v[168:171], v[90:93], v[18:21]
	s_waitcnt lgkmcnt(1)
	v_mfma_f32_16x16x32_bf16 v[14:17], v[164:167], v[94:97], v[14:17]
	v_mfma_f32_16x16x32_bf16 v[2:5], v[168:171], v[94:97], v[2:5]
	s_waitcnt lgkmcnt(0)
	v_mfma_f32_16x16x32_bf16 v[10:13], v[164:167], v[98:101], v[10:13]
	v_mfma_f32_16x16x32_bf16 v[6:9], v[168:171], v[98:101], v[6:9]
	v_lshlrev_b32_e32 v66, 5, v76
	v_lshlrev_b32_e32 v62, 2, v79
	v_or_b32_e32 v62, v62, v66
	v_ashrrev_i32_e32 v63, 31, v62
	v_lshl_add_u64 v[76:77], v[62:63], 2, s[2:3]
	global_load_dwordx4 v[92:95], v[76:77], off
	v_readlane_b32 s40, v244, 48
	s_add_u32 s8, s40, s8
	v_readlane_b32 s46, v244, 49
	s_addc_u32 s9, s46, s9
	v_lshlrev_b32_e32 v0, 1, v0
	v_lshl_add_u64 v[96:97], s[8:9], 0, v[0:1]
	v_lshlrev_b64 v[80:81], 1, v[62:63]
	v_lshl_add_u64 v[64:65], v[96:97], 0, v[80:81]
	global_load_dwordx2 v[98:99], v[64:65], off
	v_and_b32_e32 v63, 0xffffffc0, v78
	v_add_u32_e32 v86, 0x400, v63
	v_lshl_add_u32 v89, s34, 11, v86
	v_add_u32_e32 v87, 0, v82
	v_or_b32_e32 v82, v89, v84
	v_ashrrev_i32_e32 v63, 31, v66
	v_ashrrev_i32_e32 v83, 31, v82
	v_lshlrev_b32_e32 v90, 1, v62
	v_lshl_add_u64 v[72:73], v[62:63], 2, s[2:3]
	v_lshlrev_b64 v[74:75], 1, v[62:63]
	v_lshlrev_b64 v[62:63], 6, v[82:83]
	v_add_u32_e32 v64, v87, v90
	ds_read2st64_b64 v[64:67], v64 offset1:66
	v_lshlrev_b32_e32 v78, 3, v79
	v_mov_b32_e32 v79, v1
	v_lshl_add_u64 v[62:63], s[54:55], 0, v[62:63]
	v_lshl_add_u64 v[100:101], v[62:63], 0, v[78:79]
	s_waitcnt lgkmcnt(0)
	v_lshlrev_b32_e32 v62, 16, v64
	v_and_b32_e32 v63, 0xffff0000, v64
	v_lshlrev_b32_e32 v64, 16, v65
	v_and_b32_e32 v65, 0xffff0000, v65
	v_add_u32_e32 v91, 0x2100, v87
	s_add_u32 s6, s40, s6
	s_addc_u32 s7, s46, s7
	s_waitcnt vmcnt(1)
	v_add_f32_e32 v54, v54, v92
	v_add_f32_e32 v55, v55, v93
	v_add_f32_e32 v56, v56, v94
	v_add_f32_e32 v57, v57, v95
	v_mul_f32_e32 v82, 0xbfb8aa3b, v54
	v_mul_f32_e32 v83, 0xbfb8aa3b, v55
	v_mul_f32_e32 v56, 0xbfb8aa3b, v56
	v_mul_f32_e32 v57, 0xbfb8aa3b, v57
	v_exp_f32_e32 v82, v82
	v_exp_f32_e32 v83, v83
	v_exp_f32_e32 v56, v56
	v_exp_f32_e32 v57, v57
	v_add_f32_e32 v82, 1.0, v82
	v_add_f32_e32 v83, 1.0, v83
	v_add_f32_e32 v85, 1.0, v56
	v_add_f32_e32 v88, 1.0, v57
	v_rcp_f32_e32 v56, v82
	v_rcp_f32_e32 v57, v83
	v_rcp_f32_e32 v82, v85
	v_rcp_f32_e32 v83, v88
	s_waitcnt vmcnt(0)
	v_lshlrev_b32_e32 v54, 16, v98
	v_and_b32_e32 v55, 0xffff0000, v98
	v_lshlrev_b32_e32 v92, 16, v99
	v_and_b32_e32 v93, 0xffff0000, v99
	v_pk_mul_f32 v[56:57], v[56:57], v[62:63]
	v_pk_mul_f32 v[62:63], v[82:83], v[64:65]
	v_pk_mul_f32 v[54:55], v[56:57], v[54:55]
	v_pk_mul_f32 v[56:57], v[62:63], v[92:93]
	v_cvt_pk_bf16_f32 v54, v54, v55
	v_cvt_pk_bf16_f32 v55, v56, v57
	global_store_dwordx2 v[100:101], v[54:55], off
	global_load_dwordx4 v[62:65], v[72:73], off offset:64
	v_lshl_add_u64 v[54:55], v[96:97], 0, v[74:75]
	global_load_dwordx2 v[92:93], v[54:55], off offset:32
	v_or_b32_e32 v88, 32, v90
	v_add_u32_e32 v54, v87, v88
	ds_read2st64_b64 v[54:57], v54 offset1:66
	v_or_b32_e32 v85, 16, v84
	v_mov_b32_e32 v83, v1
	v_lshlrev_b32_e32 v82, 9, v85
	v_lshl_add_u64 v[94:95], s[8:9], 0, v[82:83]
	s_waitcnt lgkmcnt(0)
	v_lshlrev_b32_e32 v96, 16, v54
	v_and_b32_e32 v97, 0xffff0000, v54
	v_lshlrev_b32_e32 v54, 16, v55
	v_and_b32_e32 v55, 0xffff0000, v55
	s_waitcnt vmcnt(1)
	v_add_f32_e32 v62, v58, v62
	v_add_f32_e32 v63, v59, v63
	v_add_f32_e32 v60, v60, v64
	v_add_f32_e32 v61, v61, v65
	v_mul_f32_e32 v62, 0xbfb8aa3b, v62
	v_mul_f32_e32 v63, 0xbfb8aa3b, v63
	v_mul_f32_e32 v60, 0xbfb8aa3b, v60
	v_mul_f32_e32 v61, 0xbfb8aa3b, v61
	v_exp_f32_e32 v62, v62
	v_exp_f32_e32 v63, v63
	v_exp_f32_e32 v60, v60
	v_exp_f32_e32 v61, v61
	v_add_f32_e32 v62, 1.0, v62
	v_add_f32_e32 v63, 1.0, v63
	v_add_f32_e32 v64, 1.0, v60
	v_add_f32_e32 v65, 1.0, v61
	v_rcp_f32_e32 v60, v62
	v_rcp_f32_e32 v61, v63
	v_rcp_f32_e32 v62, v64
	v_rcp_f32_e32 v63, v65
	s_waitcnt vmcnt(0)
	v_lshlrev_b32_e32 v58, 16, v92
	v_and_b32_e32 v59, 0xffff0000, v92
	v_lshlrev_b32_e32 v64, 16, v93
	v_and_b32_e32 v65, 0xffff0000, v93
	v_pk_mul_f32 v[60:61], v[60:61], v[96:97]
	v_pk_mul_f32 v[54:55], v[62:63], v[54:55]
	v_pk_mul_f32 v[58:59], v[60:61], v[58:59]
	v_pk_mul_f32 v[54:55], v[54:55], v[64:65]
	v_cvt_pk_bf16_f32 v58, v58, v59
	v_cvt_pk_bf16_f32 v59, v54, v55
	global_store_dwordx2 v[100:101], v[58:59], off offset:32
	v_lshl_add_u64 v[54:55], v[94:95], 0, v[80:81]
	global_load_dwordx4 v[62:65], v[76:77], off
	v_add_u32_e32 v58, v91, v90
	global_load_dwordx2 v[54:55], v[54:55], off
	ds_read2st64_b64 v[58:61], v58 offset1:66
	v_or_b32_e32 v92, v89, v85
	v_ashrrev_i32_e32 v93, 31, v92
	v_lshlrev_b64 v[92:93], 6, v[92:93]
	v_lshl_add_u64 v[92:93], s[54:55], 0, v[92:93]
	s_waitcnt lgkmcnt(0)
; DI unsigned pk2(float lo, float hi) { const f32x2 v = {lo, hi}; const bf16x2_t b = __builtin_convertvector(v, bf16x2_t); return __builtin_bit_cast(unsigned, b); }
; DI float bf2f(unsigned b) { return __uint_as_float(b << 16); }
; DI float sigmoid_f(float x) { return __builtin_amdgcn_rcpf(1.f + __builtin_amdgcn_exp2f(x * -1.44269504089f)); }
; DI size_t y_off(int tok, int col) { return ((size_t)(((tok >> 6) * 32 + (col >> 5)) * 64 + (tok & 63))) * 32 + (col & 31); }
; template <int NT2>
; DI void glu_prologue(const Params& p, char* lds, int l, int tile0, int tile1) {
;     ...
;     for (int tt = 0; tt < NT2; ++tt) {
;         const int tile = tt ? tile1 : tile0;
;         const char* Ys = lds + tt * 33792;
;         const bf16_t* sg = WS_PTR(const bf16_t, OFF_SG) + (size_t)tile * 64 * 256;
; #pragma unroll
;         for (int mt = 0; mt < 4; ++mt) {
;             const int tok = mt * 16 + l15;
; #pragma unroll
;             for (int nt = 0; nt < 2; ++nt) {
;                 const int n0 = wid * 32 + nt * 16 + quad * 4;
;                 const f32x4 gb = *(const f32x4*)(p.glu_b + l * 256 + n0);
;                 const u32x2 yv = *(const u32x2*)(Ys + tok * 528 + n0 * 2);
;                 const u32x2 sv = *(const u32x2*)(sg + (size_t)tok * 256 + n0);
;                 float o[4];
;                 o[0] = sigmoid_f(acc[tt][mt][nt][0] + gb[0]) * bf2f(yv[0] & 0xffffu) * bf2f(sv[0] & 0xffffu);
;                 o[1] = sigmoid_f(acc[tt][mt][nt][1] + gb[1]) * bf2f(yv[0] >> 16) * bf2f(sv[0] >> 16);
;                 o[2] = sigmoid_f(acc[tt][mt][nt][2] + gb[2]) * bf2f(yv[1] & 0xffffu) * bf2f(sv[1] & 0xffffu);
;                 o[3] = sigmoid_f(acc[tt][mt][nt][3] + gb[3]) * bf2f(yv[1] >> 16) * bf2f(sv[1] >> 16);
;                 *(u32x2*)(yo + y_off(tile * 64 + tok, 512 + n0)) = (u32x2){pk2(o[0], o[1]), pk2(o[2], o[3])};
;             }
	v_lshlrev_b32_e32 v96, 16, v58
	v_and_b32_e32 v97, 0xffff0000, v58
	v_lshlrev_b32_e32 v58, 16, v59
	v_and_b32_e32 v59, 0xffff0000, v59
	v_lshl_add_u64 v[92:93], v[92:93], 0, v[78:79]
	s_waitcnt vmcnt(1)
	v_add_f32_e32 v68, v68, v62
	v_add_f32_e32 v69, v69, v63
	s_waitcnt vmcnt(0)
	v_lshlrev_b32_e32 v62, 16, v54
	v_and_b32_e32 v63, 0xffff0000, v54
	v_add_f32_e32 v54, v70, v64
	v_add_f32_e32 v64, v71, v65
	v_mul_f32_e32 v65, 0xbfb8aa3b, v68
	v_mul_f32_e32 v68, 0xbfb8aa3b, v69
	v_mul_f32_e32 v54, 0xbfb8aa3b, v54
	v_mul_f32_e32 v64, 0xbfb8aa3b, v64
	v_exp_f32_e32 v65, v65
	v_exp_f32_e32 v68, v68
	v_exp_f32_e32 v54, v54
	v_exp_f32_e32 v64, v64
	v_add_f32_e32 v65, 1.0, v65
	v_add_f32_e32 v68, 1.0, v68
	v_add_f32_e32 v54, 1.0, v54
	v_add_f32_e32 v69, 1.0, v64
	v_rcp_f32_e32 v64, v65
	v_rcp_f32_e32 v65, v68
	v_rcp_f32_e32 v68, v54
	v_rcp_f32_e32 v69, v69
	v_lshlrev_b32_e32 v54, 16, v55
	v_and_b32_e32 v55, 0xffff0000, v55
	v_pk_mul_f32 v[64:65], v[64:65], v[96:97]
	v_pk_mul_f32 v[58:59], v[68:69], v[58:59]
	v_pk_mul_f32 v[62:63], v[64:65], v[62:63]
	v_pk_mul_f32 v[54:55], v[58:59], v[54:55]
	v_cvt_pk_bf16_f32 v58, v62, v63
	v_cvt_pk_bf16_f32 v59, v54, v55
	global_store_dwordx2 v[92:93], v[58:59], off
	global_load_dwordx4 v[68:71], v[72:73], off offset:64
	v_lshl_add_u64 v[54:55], v[94:95], 0, v[74:75]
	global_load_dwordx2 v[94:95], v[54:55], off offset:32
	v_add_u32_e32 v54, v91, v88
	ds_read2st64_b64 v[62:65], v54 offset1:66
	v_or_b32_e32 v58, 32, v84
	v_mov_b32_e32 v55, v1
	v_lshlrev_b32_e32 v54, 9, v58
	v_lshl_add_u64 v[96:97], s[8:9], 0, v[54:55]
	s_waitcnt lgkmcnt(0)
	v_lshlrev_b32_e32 v98, 16, v62
	v_and_b32_e32 v99, 0xffff0000, v62
	v_lshlrev_b32_e32 v62, 16, v63
	v_and_b32_e32 v63, 0xffff0000, v63
	s_waitcnt vmcnt(1)
	v_add_f32_e32 v59, v50, v68
	v_add_f32_e32 v68, v51, v69
	v_add_f32_e32 v52, v52, v70
	v_add_f32_e32 v53, v53, v71
	v_mul_f32_e32 v59, 0xbfb8aa3b, v59
	v_mul_f32_e32 v68, 0xbfb8aa3b, v68
	v_mul_f32_e32 v52, 0xbfb8aa3b, v52
	v_mul_f32_e32 v53, 0xbfb8aa3b, v53
	v_exp_f32_e32 v59, v59
	v_exp_f32_e32 v68, v68
	v_exp_f32_e32 v52, v52
	v_exp_f32_e32 v53, v53
	v_add_f32_e32 v59, 1.0, v59
	v_add_f32_e32 v68, 1.0, v68
	v_add_f32_e32 v69, 1.0, v52
	v_add_f32_e32 v70, 1.0, v53
	v_rcp_f32_e32 v52, v59
	v_rcp_f32_e32 v53, v68
	v_rcp_f32_e32 v68, v69
	v_rcp_f32_e32 v69, v70
	s_waitcnt vmcnt(0)
	v_lshlrev_b32_e32 v50, 16, v94
	v_and_b32_e32 v51, 0xffff0000, v94
	v_lshlrev_b32_e32 v70, 16, v95
	v_and_b32_e32 v71, 0xffff0000, v95
	v_pk_mul_f32 v[52:53], v[52:53], v[98:99]
	v_pk_mul_f32 v[62:63], v[68:69], v[62:63]
	v_pk_mul_f32 v[50:51], v[52:53], v[50:51]
	v_pk_mul_f32 v[52:53], v[62:63], v[70:71]
	v_cvt_pk_bf16_f32 v50, v50, v51
	v_cvt_pk_bf16_f32 v51, v52, v53
	global_store_dwordx2 v[92:93], v[50:51], off offset:32
	global_load_dwordx4 v[68:71], v[76:77], off
	v_lshl_add_u64 v[50:51], v[96:97], 0, v[80:81]
	global_load_dwordx2 v[62:63], v[50:51], off
	v_add_u32_e32 v59, 0x4200, v87
	v_add_u32_e32 v50, v59, v90
	ds_read2st64_b64 v[50:53], v50 offset1:66
	v_or_b32_e32 v92, v89, v58
	v_ashrrev_i32_e32 v93, 31, v92
	v_lshlrev_b64 v[92:93], 6, v[92:93]
	v_lshl_add_u64 v[92:93], s[54:55], 0, v[92:93]
	s_waitcnt lgkmcnt(0)
	v_lshlrev_b32_e32 v94, 16, v50
	v_and_b32_e32 v95, 0xffff0000, v50
	v_lshlrev_b32_e32 v50, 16, v51
	v_and_b32_e32 v51, 0xffff0000, v51
	v_lshl_add_u64 v[92:93], v[92:93], 0, v[78:79]
	v_add_u32_e32 v87, 0x6300, v87
	s_waitcnt vmcnt(1)
	v_add_f32_e32 v68, v46, v68
	v_add_f32_e32 v69, v47, v69
	v_add_f32_e32 v48, v48, v70
	v_add_f32_e32 v49, v49, v71
	s_waitcnt vmcnt(0)
	v_lshlrev_b32_e32 v46, 16, v62
	v_and_b32_e32 v47, 0xffff0000, v62
	v_mul_f32_e32 v62, 0xbfb8aa3b, v68
	v_mul_f32_e32 v68, 0xbfb8aa3b, v69
	v_mul_f32_e32 v48, 0xbfb8aa3b, v48
	v_mul_f32_e32 v49, 0xbfb8aa3b, v49
	v_exp_f32_e32 v62, v62
	v_exp_f32_e32 v68, v68
	v_exp_f32_e32 v48, v48
	v_exp_f32_e32 v49, v49
	v_add_f32_e32 v62, 1.0, v62
	v_add_f32_e32 v68, 1.0, v68
	v_add_f32_e32 v69, 1.0, v48
	v_add_f32_e32 v70, 1.0, v49
	v_rcp_f32_e32 v48, v62
	v_rcp_f32_e32 v49, v68
	v_rcp_f32_e32 v68, v69
	v_rcp_f32_e32 v69, v70
	v_lshlrev_b32_e32 v62, 16, v63
	v_and_b32_e32 v63, 0xffff0000, v63
	v_pk_mul_f32 v[48:49], v[48:49], v[94:95]
	v_pk_mul_f32 v[50:51], v[68:69], v[50:51]
	v_pk_mul_f32 v[46:47], v[48:49], v[46:47]
	v_pk_mul_f32 v[48:49], v[50:51], v[62:63]
	v_cvt_pk_bf16_f32 v46, v46, v47
	v_cvt_pk_bf16_f32 v47, v48, v49
	global_store_dwordx2 v[92:93], v[46:47], off
	global_load_dwordx4 v[68:71], v[72:73], off offset:64
	v_lshl_add_u64 v[46:47], v[96:97], 0, v[74:75]
	global_load_dwordx2 v[62:63], v[46:47], off offset:32
	v_add_u32_e32 v46, v59, v88
	ds_read2st64_b64 v[46:49], v46 offset1:66
	v_or_b32_e32 v59, 48, v84
	v_mov_b32_e32 v51, v1
	v_lshlrev_b32_e32 v50, 9, v59
	v_lshl_add_u64 v[94:95], s[8:9], 0, v[50:51]
	s_waitcnt lgkmcnt(0)
	v_lshlrev_b32_e32 v96, 16, v46
	v_and_b32_e32 v97, 0xffff0000, v46
	v_lshlrev_b32_e32 v46, 16, v47
	v_and_b32_e32 v47, 0xffff0000, v47
	s_waitcnt vmcnt(1)
	v_add_f32_e32 v68, v42, v68
	v_add_f32_e32 v69, v43, v69
	v_add_f32_e32 v44, v44, v70
	v_add_f32_e32 v45, v45, v71
	s_waitcnt vmcnt(0)
; DI unsigned pk2(float lo, float hi) { const f32x2 v = {lo, hi}; const bf16x2_t b = __builtin_convertvector(v, bf16x2_t); return __builtin_bit_cast(unsigned, b); }
; DI float bf2f(unsigned b) { return __uint_as_float(b << 16); }
; DI float sigmoid_f(float x) { return __builtin_amdgcn_rcpf(1.f + __builtin_amdgcn_exp2f(x * -1.44269504089f)); }
; DI size_t y_off(int tok, int col) { return ((size_t)(((tok >> 6) * 32 + (col >> 5)) * 64 + (tok & 63))) * 32 + (col & 31); }
; template <int NT2>
; DI void glu_prologue(const Params& p, char* lds, int l, int tile0, int tile1) {
;     ...
;     for (int tt = 0; tt < NT2; ++tt) {
;         const int tile = tt ? tile1 : tile0;
;         const char* Ys = lds + tt * 33792;
;         const bf16_t* sg = WS_PTR(const bf16_t, OFF_SG) + (size_t)tile * 64 * 256;
; #pragma unroll
;         for (int mt = 0; mt < 4; ++mt) {
;             const int tok = mt * 16 + l15;
; #pragma unroll
;             for (int nt = 0; nt < 2; ++nt) {
;                 const int n0 = wid * 32 + nt * 16 + quad * 4;
;                 const f32x4 gb = *(const f32x4*)(p.glu_b + l * 256 + n0);
;                 const u32x2 yv = *(const u32x2*)(Ys + tok * 528 + n0 * 2);
;                 const u32x2 sv = *(const u32x2*)(sg + (size_t)tok * 256 + n0);
;                 float o[4];
;                 o[0] = sigmoid_f(acc[tt][mt][nt][0] + gb[0]) * bf2f(yv[0] & 0xffffu) * bf2f(sv[0] & 0xffffu);
;                 o[1] = sigmoid_f(acc[tt][mt][nt][1] + gb[1]) * bf2f(yv[0] >> 16) * bf2f(sv[0] >> 16);
;                 o[2] = sigmoid_f(acc[tt][mt][nt][2] + gb[2]) * bf2f(yv[1] & 0xffffu) * bf2f(sv[1] & 0xffffu);
;                 o[3] = sigmoid_f(acc[tt][mt][nt][3] + gb[3]) * bf2f(yv[1] >> 16) * bf2f(sv[1] >> 16);
;                 *(u32x2*)(yo + y_off(tile * 64 + tok, 512 + n0)) = (u32x2){pk2(o[0], o[1]), pk2(o[2], o[3])};
;             }
	v_lshlrev_b32_e32 v42, 16, v62
	v_and_b32_e32 v43, 0xffff0000, v62
	v_mul_f32_e32 v62, 0xbfb8aa3b, v68
	v_mul_f32_e32 v68, 0xbfb8aa3b, v69
	v_mul_f32_e32 v44, 0xbfb8aa3b, v44
	v_mul_f32_e32 v45, 0xbfb8aa3b, v45
	v_exp_f32_e32 v62, v62
	v_exp_f32_e32 v68, v68
	v_exp_f32_e32 v44, v44
	v_exp_f32_e32 v45, v45
	v_add_f32_e32 v62, 1.0, v62
	v_add_f32_e32 v68, 1.0, v68
	v_add_f32_e32 v69, 1.0, v44
	v_add_f32_e32 v70, 1.0, v45
	v_rcp_f32_e32 v44, v62
	v_rcp_f32_e32 v45, v68
	v_rcp_f32_e32 v68, v69
	v_rcp_f32_e32 v69, v70
	v_lshlrev_b32_e32 v62, 16, v63
	v_and_b32_e32 v63, 0xffff0000, v63
	v_pk_mul_f32 v[44:45], v[44:45], v[96:97]
	v_pk_mul_f32 v[46:47], v[68:69], v[46:47]
	v_pk_mul_f32 v[42:43], v[44:45], v[42:43]
	v_pk_mul_f32 v[44:45], v[46:47], v[62:63]
	v_cvt_pk_bf16_f32 v42, v42, v43
	v_cvt_pk_bf16_f32 v43, v44, v45
	global_store_dwordx2 v[92:93], v[42:43], off offset:32
	global_load_dwordx4 v[68:71], v[76:77], off
	v_lshl_add_u64 v[42:43], v[94:95], 0, v[80:81]
	global_load_dwordx2 v[46:47], v[42:43], off
	v_add_u32_e32 v42, v87, v90
	ds_read2st64_b64 v[42:45], v42 offset1:66
	v_or_b32_e32 v62, v89, v59
	v_ashrrev_i32_e32 v63, 31, v62
	v_lshlrev_b64 v[62:63], 6, v[62:63]
	v_lshl_add_u64 v[62:63], s[54:55], 0, v[62:63]
	s_waitcnt lgkmcnt(0)
	v_lshlrev_b32_e32 v90, 16, v42
	v_and_b32_e32 v91, 0xffff0000, v42
	v_lshlrev_b32_e32 v42, 16, v43
	v_and_b32_e32 v43, 0xffff0000, v43
	v_lshl_add_u64 v[62:63], v[62:63], 0, v[78:79]
	s_waitcnt vmcnt(1)
	v_add_f32_e32 v68, v38, v68
	v_add_f32_e32 v69, v39, v69
	v_add_f32_e32 v40, v40, v70
	v_add_f32_e32 v41, v41, v71
	s_waitcnt vmcnt(0)
	v_lshlrev_b32_e32 v38, 16, v46
	v_and_b32_e32 v39, 0xffff0000, v46
	v_mul_f32_e32 v46, 0xbfb8aa3b, v68
	v_mul_f32_e32 v68, 0xbfb8aa3b, v69
	v_mul_f32_e32 v40, 0xbfb8aa3b, v40
	v_mul_f32_e32 v41, 0xbfb8aa3b, v41
	v_exp_f32_e32 v46, v46
	v_exp_f32_e32 v68, v68
	v_exp_f32_e32 v40, v40
	v_exp_f32_e32 v41, v41
	v_add_f32_e32 v46, 1.0, v46
	v_add_f32_e32 v68, 1.0, v68
	v_add_f32_e32 v69, 1.0, v40
	v_add_f32_e32 v70, 1.0, v41
	v_rcp_f32_e32 v40, v46
	v_rcp_f32_e32 v41, v68
	v_rcp_f32_e32 v68, v69
	v_rcp_f32_e32 v69, v70
	v_lshlrev_b32_e32 v46, 16, v47
	v_and_b32_e32 v47, 0xffff0000, v47
	v_pk_mul_f32 v[40:41], v[40:41], v[90:91]
	v_pk_mul_f32 v[42:43], v[68:69], v[42:43]
	v_pk_mul_f32 v[38:39], v[40:41], v[38:39]
	v_pk_mul_f32 v[40:41], v[42:43], v[46:47]
	v_cvt_pk_bf16_f32 v38, v38, v39
	v_cvt_pk_bf16_f32 v39, v40, v41
	global_store_dwordx2 v[62:63], v[38:39], off
	global_load_dwordx4 v[68:71], v[72:73], off offset:64
	v_lshl_add_u64 v[38:39], v[94:95], 0, v[74:75]
	global_load_dwordx2 v[42:43], v[38:39], off offset:32
	v_lshl_add_u64 v[46:47], s[6:7], 0, v[0:1]
	v_add_u32_e32 v38, v87, v88
	ds_read2st64_b64 v[38:41], v38 offset1:66
	s_waitcnt lgkmcnt(0)
	v_lshlrev_b32_e32 v88, 16, v38
	v_and_b32_e32 v89, 0xffff0000, v38
	v_lshlrev_b32_e32 v38, 16, v39
	v_and_b32_e32 v39, 0xffff0000, v39
	s_waitcnt vmcnt(1)
	v_add_f32_e32 v0, v30, v68
	v_add_f32_e32 v68, v31, v69
	v_add_f32_e32 v32, v32, v70
	v_add_f32_e32 v33, v33, v71
	s_waitcnt vmcnt(0)
	v_lshlrev_b32_e32 v30, 16, v42
	v_and_b32_e32 v31, 0xffff0000, v42
	v_mul_f32_e32 v0, 0xbfb8aa3b, v0
	v_mul_f32_e32 v42, 0xbfb8aa3b, v68
	v_mul_f32_e32 v32, 0xbfb8aa3b, v32
	v_mul_f32_e32 v33, 0xbfb8aa3b, v33
	v_exp_f32_e32 v0, v0
	v_exp_f32_e32 v42, v42
	v_exp_f32_e32 v32, v32
	v_exp_f32_e32 v33, v33
	v_add_f32_e32 v0, 1.0, v0
	v_add_f32_e32 v42, 1.0, v42
	v_add_f32_e32 v68, 1.0, v32
	v_add_f32_e32 v69, 1.0, v33
	v_rcp_f32_e32 v32, v0
	v_rcp_f32_e32 v33, v42
	v_rcp_f32_e32 v68, v68
	v_rcp_f32_e32 v69, v69
	v_lshlrev_b32_e32 v42, 16, v43
	v_and_b32_e32 v43, 0xffff0000, v43
	v_pk_mul_f32 v[32:33], v[32:33], v[88:89]
	v_pk_mul_f32 v[38:39], v[68:69], v[38:39]
	v_pk_mul_f32 v[30:31], v[32:33], v[30:31]
	v_pk_mul_f32 v[32:33], v[38:39], v[42:43]
	v_cvt_pk_bf16_f32 v30, v30, v31
	v_cvt_pk_bf16_f32 v31, v32, v33
	global_store_dwordx2 v[62:63], v[30:31], off offset:32
	global_load_dwordx4 v[30:33], v[76:77], off
	v_lshl_add_u64 v[38:39], v[46:47], 0, v[80:81]
	global_load_dwordx2 v[38:39], v[38:39], off
	v_lshl_add_u32 v0, s48, 11, v86
	v_or_b32_e32 v42, v0, v84
	v_ashrrev_i32_e32 v43, 31, v42
	v_lshlrev_b32_e32 v62, 16, v66
	v_and_b32_e32 v63, 0xffff0000, v66
	v_lshlrev_b32_e32 v66, 16, v67
	v_and_b32_e32 v67, 0xffff0000, v67
	v_lshlrev_b64 v[42:43], 6, v[42:43]
	v_lshl_add_u64 v[42:43], s[54:55], 0, v[42:43]
	v_lshl_add_u64 v[42:43], v[42:43], 0, v[78:79]
	s_waitcnt vmcnt(1)
	v_add_f32_e32 v34, v34, v30
	v_add_f32_e32 v35, v35, v31
	v_add_f32_e32 v32, v36, v32
	v_add_f32_e32 v33, v37, v33
	v_mul_f32_e32 v34, 0xbfb8aa3b, v34
	v_mul_f32_e32 v35, 0xbfb8aa3b, v35
	v_mul_f32_e32 v32, 0xbfb8aa3b, v32
	v_mul_f32_e32 v33, 0xbfb8aa3b, v33
	v_exp_f32_e32 v34, v34
	v_exp_f32_e32 v35, v35
	v_exp_f32_e32 v32, v32
	v_exp_f32_e32 v33, v33
	v_add_f32_e32 v34, 1.0, v34
	v_add_f32_e32 v35, 1.0, v35
	v_add_f32_e32 v36, 1.0, v32
	v_add_f32_e32 v37, 1.0, v33
	v_rcp_f32_e32 v32, v34
	v_rcp_f32_e32 v33, v35
	v_rcp_f32_e32 v34, v36
	v_rcp_f32_e32 v35, v37
	s_waitcnt vmcnt(0)
	v_lshlrev_b32_e32 v30, 16, v38
	v_and_b32_e32 v31, 0xffff0000, v38
	v_lshlrev_b32_e32 v36, 16, v39
	v_and_b32_e32 v37, 0xffff0000, v39
	v_pk_mul_f32 v[32:33], v[32:33], v[62:63]
	v_pk_mul_f32 v[34:35], v[34:35], v[66:67]
	v_pk_mul_f32 v[30:31], v[32:33], v[30:31]
	v_pk_mul_f32 v[32:33], v[34:35], v[36:37]
	v_cvt_pk_bf16_f32 v30, v30, v31
	v_cvt_pk_bf16_f32 v31, v32, v33
	global_store_dwordx2 v[42:43], v[30:31], off
	global_load_dwordx4 v[30:33], v[72:73], off offset:64
	v_lshl_add_u64 v[34:35], v[46:47], 0, v[74:75]
	global_load_dwordx2 v[34:35], v[34:35], off offset:32
	v_lshlrev_b32_e32 v38, 16, v56
	v_and_b32_e32 v39, 0xffff0000, v56
	v_lshlrev_b32_e32 v46, 16, v57
	v_and_b32_e32 v47, 0xffff0000, v57
	v_lshl_add_u64 v[36:37], s[6:7], 0, v[82:83]
	s_waitcnt vmcnt(1)
; DI unsigned pk2(float lo, float hi) { const f32x2 v = {lo, hi}; const bf16x2_t b = __builtin_convertvector(v, bf16x2_t); return __builtin_bit_cast(unsigned, b); }
; DI float bf2f(unsigned b) { return __uint_as_float(b << 16); }
; DI float sigmoid_f(float x) { return __builtin_amdgcn_rcpf(1.f + __builtin_amdgcn_exp2f(x * -1.44269504089f)); }
; DI size_t y_off(int tok, int col) { return ((size_t)(((tok >> 6) * 32 + (col >> 5)) * 64 + (tok & 63))) * 32 + (col & 31); }
; template <int NT2>
; DI void glu_prologue(const Params& p, char* lds, int l, int tile0, int tile1) {
;     ...
;     for (int tt = 0; tt < NT2; ++tt) {
;         const int tile = tt ? tile1 : tile0;
;         const char* Ys = lds + tt * 33792;
;         const bf16_t* sg = WS_PTR(const bf16_t, OFF_SG) + (size_t)tile * 64 * 256;
; #pragma unroll
;         for (int mt = 0; mt < 4; ++mt) {
;             const int tok = mt * 16 + l15;
; #pragma unroll
;             for (int nt = 0; nt < 2; ++nt) {
;                 const int n0 = wid * 32 + nt * 16 + quad * 4;
;                 const f32x4 gb = *(const f32x4*)(p.glu_b + l * 256 + n0);
;                 const u32x2 yv = *(const u32x2*)(Ys + tok * 528 + n0 * 2);
;                 const u32x2 sv = *(const u32x2*)(sg + (size_t)tok * 256 + n0);
;                 float o[4];
;                 o[0] = sigmoid_f(acc[tt][mt][nt][0] + gb[0]) * bf2f(yv[0] & 0xffffu) * bf2f(sv[0] & 0xffffu);
;                 o[1] = sigmoid_f(acc[tt][mt][nt][1] + gb[1]) * bf2f(yv[0] >> 16) * bf2f(sv[0] >> 16);
;                 o[2] = sigmoid_f(acc[tt][mt][nt][2] + gb[2]) * bf2f(yv[1] & 0xffffu) * bf2f(sv[1] & 0xffffu);
;                 o[3] = sigmoid_f(acc[tt][mt][nt][3] + gb[3]) * bf2f(yv[1] >> 16) * bf2f(sv[1] >> 16);
;                 *(u32x2*)(yo + y_off(tile * 64 + tok, 512 + n0)) = (u32x2){pk2(o[0], o[1]), pk2(o[2], o[3])};
;             }
	v_add_f32_e32 v30, v26, v30
	v_add_f32_e32 v31, v27, v31
	v_add_f32_e32 v28, v28, v32
	v_add_f32_e32 v29, v29, v33
	v_mul_f32_e32 v30, 0xbfb8aa3b, v30
	v_mul_f32_e32 v31, 0xbfb8aa3b, v31
	v_mul_f32_e32 v28, 0xbfb8aa3b, v28
	v_mul_f32_e32 v29, 0xbfb8aa3b, v29
	v_exp_f32_e32 v30, v30
	v_exp_f32_e32 v31, v31
	v_exp_f32_e32 v28, v28
	v_exp_f32_e32 v29, v29
	v_add_f32_e32 v30, 1.0, v30
	v_add_f32_e32 v31, 1.0, v31
	v_add_f32_e32 v32, 1.0, v28
	v_add_f32_e32 v33, 1.0, v29
	v_rcp_f32_e32 v28, v30
	v_rcp_f32_e32 v29, v31
	v_rcp_f32_e32 v30, v32
	v_rcp_f32_e32 v31, v33
	s_waitcnt vmcnt(0)
	v_lshlrev_b32_e32 v26, 16, v34
	v_and_b32_e32 v27, 0xffff0000, v34
	v_lshlrev_b32_e32 v32, 16, v35
	v_and_b32_e32 v33, 0xffff0000, v35
	v_pk_mul_f32 v[28:29], v[28:29], v[38:39]
	v_pk_mul_f32 v[30:31], v[30:31], v[46:47]
	v_pk_mul_f32 v[26:27], v[28:29], v[26:27]
	v_pk_mul_f32 v[28:29], v[30:31], v[32:33]
	v_cvt_pk_bf16_f32 v26, v26, v27
	v_cvt_pk_bf16_f32 v27, v28, v29
	global_store_dwordx2 v[42:43], v[26:27], off offset:32
	global_load_dwordx4 v[26:29], v[76:77], off
	v_lshl_add_u64 v[30:31], v[36:37], 0, v[80:81]
	global_load_dwordx2 v[30:31], v[30:31], off
	v_or_b32_e32 v32, v0, v85
	v_ashrrev_i32_e32 v33, 31, v32
	v_lshlrev_b32_e32 v34, 16, v60
	v_and_b32_e32 v35, 0xffff0000, v60
	v_lshlrev_b32_e32 v38, 16, v61
	v_and_b32_e32 v39, 0xffff0000, v61
	v_lshlrev_b64 v[32:33], 6, v[32:33]
	v_lshl_add_u64 v[32:33], s[54:55], 0, v[32:33]
	v_lshl_add_u64 v[32:33], v[32:33], 0, v[78:79]
	s_waitcnt vmcnt(1)
	v_add_f32_e32 v26, v22, v26
	v_add_f32_e32 v27, v23, v27
	v_add_f32_e32 v24, v24, v28
	v_add_f32_e32 v25, v25, v29
	v_mul_f32_e32 v26, 0xbfb8aa3b, v26
	v_mul_f32_e32 v27, 0xbfb8aa3b, v27
	v_mul_f32_e32 v24, 0xbfb8aa3b, v24
	v_mul_f32_e32 v25, 0xbfb8aa3b, v25
	v_exp_f32_e32 v26, v26
	v_exp_f32_e32 v27, v27
	v_exp_f32_e32 v24, v24
	v_exp_f32_e32 v25, v25
	v_add_f32_e32 v26, 1.0, v26
	v_add_f32_e32 v27, 1.0, v27
	v_add_f32_e32 v28, 1.0, v24
	v_add_f32_e32 v29, 1.0, v25
	v_rcp_f32_e32 v24, v26
	v_rcp_f32_e32 v25, v27
	v_rcp_f32_e32 v26, v28
	v_rcp_f32_e32 v27, v29
	s_waitcnt vmcnt(0)
	v_lshlrev_b32_e32 v22, 16, v30
	v_and_b32_e32 v23, 0xffff0000, v30
	v_lshlrev_b32_e32 v28, 16, v31
	v_and_b32_e32 v29, 0xffff0000, v31
	v_pk_mul_f32 v[24:25], v[24:25], v[34:35]
	v_pk_mul_f32 v[26:27], v[26:27], v[38:39]
	v_pk_mul_f32 v[22:23], v[24:25], v[22:23]
	v_pk_mul_f32 v[24:25], v[26:27], v[28:29]
	v_cvt_pk_bf16_f32 v22, v22, v23
	v_cvt_pk_bf16_f32 v23, v24, v25
	global_store_dwordx2 v[32:33], v[22:23], off
	global_load_dwordx4 v[22:25], v[72:73], off offset:64
	v_lshl_add_u64 v[26:27], v[36:37], 0, v[74:75]
	global_load_dwordx2 v[26:27], v[26:27], off offset:32
	v_lshlrev_b32_e32 v30, 16, v64
	v_and_b32_e32 v31, 0xffff0000, v64
	v_lshlrev_b32_e32 v34, 16, v65
	v_and_b32_e32 v35, 0xffff0000, v65
	v_lshl_add_u64 v[28:29], s[6:7], 0, v[54:55]
	s_waitcnt vmcnt(1)
	v_add_f32_e32 v22, v18, v22
	v_add_f32_e32 v23, v19, v23
	v_add_f32_e32 v20, v20, v24
	v_add_f32_e32 v21, v21, v25
	v_mul_f32_e32 v22, 0xbfb8aa3b, v22
	v_mul_f32_e32 v23, 0xbfb8aa3b, v23
	v_mul_f32_e32 v20, 0xbfb8aa3b, v20
	v_mul_f32_e32 v21, 0xbfb8aa3b, v21
	v_exp_f32_e32 v22, v22
	v_exp_f32_e32 v23, v23
	v_exp_f32_e32 v20, v20
	v_exp_f32_e32 v21, v21
	v_add_f32_e32 v22, 1.0, v22
	v_add_f32_e32 v23, 1.0, v23
	v_add_f32_e32 v24, 1.0, v20
	v_add_f32_e32 v25, 1.0, v21
	v_rcp_f32_e32 v20, v22
	v_rcp_f32_e32 v21, v23
	v_rcp_f32_e32 v22, v24
	v_rcp_f32_e32 v23, v25
	s_waitcnt vmcnt(0)
	v_lshlrev_b32_e32 v18, 16, v26
	v_and_b32_e32 v19, 0xffff0000, v26
	v_lshlrev_b32_e32 v24, 16, v27
	v_and_b32_e32 v25, 0xffff0000, v27
	v_pk_mul_f32 v[20:21], v[20:21], v[30:31]
	v_pk_mul_f32 v[22:23], v[22:23], v[34:35]
	v_pk_mul_f32 v[18:19], v[20:21], v[18:19]
	v_pk_mul_f32 v[20:21], v[22:23], v[24:25]
	v_cvt_pk_bf16_f32 v18, v18, v19
	v_cvt_pk_bf16_f32 v19, v20, v21
	global_store_dwordx2 v[32:33], v[18:19], off offset:32
	global_load_dwordx4 v[18:21], v[76:77], off
	v_lshl_add_u64 v[22:23], v[28:29], 0, v[80:81]
	global_load_dwordx2 v[22:23], v[22:23], off
	v_or_b32_e32 v24, v0, v58
	v_ashrrev_i32_e32 v25, 31, v24
	v_lshlrev_b32_e32 v26, 16, v52
	v_and_b32_e32 v27, 0xffff0000, v52
	v_lshlrev_b32_e32 v30, 16, v53
	v_and_b32_e32 v31, 0xffff0000, v53
	v_lshlrev_b64 v[24:25], 6, v[24:25]
	v_lshl_add_u64 v[24:25], s[54:55], 0, v[24:25]
	v_lshl_add_u64 v[24:25], v[24:25], 0, v[78:79]
	s_waitcnt vmcnt(1)
	v_add_f32_e32 v18, v14, v18
	v_add_f32_e32 v19, v15, v19
	v_add_f32_e32 v16, v16, v20
	v_add_f32_e32 v17, v17, v21
	v_mul_f32_e32 v18, 0xbfb8aa3b, v18
	v_mul_f32_e32 v19, 0xbfb8aa3b, v19
	v_mul_f32_e32 v16, 0xbfb8aa3b, v16
	v_mul_f32_e32 v17, 0xbfb8aa3b, v17
	v_exp_f32_e32 v18, v18
	v_exp_f32_e32 v19, v19
	v_exp_f32_e32 v16, v16
	v_exp_f32_e32 v17, v17
	v_add_f32_e32 v18, 1.0, v18
	v_add_f32_e32 v19, 1.0, v19
	v_add_f32_e32 v20, 1.0, v16
	v_add_f32_e32 v21, 1.0, v17
	v_rcp_f32_e32 v16, v18
	v_rcp_f32_e32 v17, v19
	v_rcp_f32_e32 v18, v20
	v_rcp_f32_e32 v19, v21
	s_waitcnt vmcnt(0)
; DI unsigned pk2(float lo, float hi) { const f32x2 v = {lo, hi}; const bf16x2_t b = __builtin_convertvector(v, bf16x2_t); return __builtin_bit_cast(unsigned, b); }
; DI float bf2f(unsigned b) { return __uint_as_float(b << 16); }
; DI float sigmoid_f(float x) { return __builtin_amdgcn_rcpf(1.f + __builtin_amdgcn_exp2f(x * -1.44269504089f)); }
; DI size_t y_off(int tok, int col) { return ((size_t)(((tok >> 6) * 32 + (col >> 5)) * 64 + (tok & 63))) * 32 + (col & 31); }
; template <int NT2>
; DI void glu_prologue(const Params& p, char* lds, int l, int tile0, int tile1) {
;     ...
;     for (int tt = 0; tt < NT2; ++tt) {
;         const int tile = tt ? tile1 : tile0;
;         const char* Ys = lds + tt * 33792;
;         const bf16_t* sg = WS_PTR(const bf16_t, OFF_SG) + (size_t)tile * 64 * 256;
; #pragma unroll
;         for (int mt = 0; mt < 4; ++mt) {
;             const int tok = mt * 16 + l15;
; #pragma unroll
;             for (int nt = 0; nt < 2; ++nt) {
;                 const int n0 = wid * 32 + nt * 16 + quad * 4;
;                 const f32x4 gb = *(const f32x4*)(p.glu_b + l * 256 + n0);
;                 const u32x2 yv = *(const u32x2*)(Ys + tok * 528 + n0 * 2);
;                 const u32x2 sv = *(const u32x2*)(sg + (size_t)tok * 256 + n0);
;                 float o[4];
;                 o[0] = sigmoid_f(acc[tt][mt][nt][0] + gb[0]) * bf2f(yv[0] & 0xffffu) * bf2f(sv[0] & 0xffffu);
;                 o[1] = sigmoid_f(acc[tt][mt][nt][1] + gb[1]) * bf2f(yv[0] >> 16) * bf2f(sv[0] >> 16);
;                 o[2] = sigmoid_f(acc[tt][mt][nt][2] + gb[2]) * bf2f(yv[1] & 0xffffu) * bf2f(sv[1] & 0xffffu);
;                 o[3] = sigmoid_f(acc[tt][mt][nt][3] + gb[3]) * bf2f(yv[1] >> 16) * bf2f(sv[1] >> 16);
;                 *(u32x2*)(yo + y_off(tile * 64 + tok, 512 + n0)) = (u32x2){pk2(o[0], o[1]), pk2(o[2], o[3])};
;             }
;         }
;     }
	v_lshlrev_b32_e32 v14, 16, v22
	v_and_b32_e32 v15, 0xffff0000, v22
	v_lshlrev_b32_e32 v20, 16, v23
	v_and_b32_e32 v21, 0xffff0000, v23
	v_pk_mul_f32 v[16:17], v[16:17], v[26:27]
	v_pk_mul_f32 v[18:19], v[18:19], v[30:31]
	v_pk_mul_f32 v[14:15], v[16:17], v[14:15]
	v_pk_mul_f32 v[16:17], v[18:19], v[20:21]
	v_cvt_pk_bf16_f32 v14, v14, v15
	v_cvt_pk_bf16_f32 v15, v16, v17
	global_store_dwordx2 v[24:25], v[14:15], off
	global_load_dwordx4 v[14:17], v[72:73], off offset:64
	v_lshl_add_u64 v[18:19], v[28:29], 0, v[74:75]
	global_load_dwordx2 v[18:19], v[18:19], off offset:32
	v_lshlrev_b32_e32 v22, 16, v48
	v_and_b32_e32 v23, 0xffff0000, v48
	v_lshlrev_b32_e32 v26, 16, v49
	v_and_b32_e32 v27, 0xffff0000, v49
	v_lshl_add_u64 v[20:21], s[6:7], 0, v[50:51]
	s_waitcnt vmcnt(1)
	v_add_f32_e32 v14, v2, v14
	v_add_f32_e32 v15, v3, v15
	v_add_f32_e32 v4, v4, v16
	v_add_f32_e32 v5, v5, v17
	v_mul_f32_e32 v14, 0xbfb8aa3b, v14
	v_mul_f32_e32 v15, 0xbfb8aa3b, v15
	v_mul_f32_e32 v4, 0xbfb8aa3b, v4
	v_mul_f32_e32 v5, 0xbfb8aa3b, v5
	v_exp_f32_e32 v14, v14
	v_exp_f32_e32 v15, v15
	v_exp_f32_e32 v4, v4
	v_exp_f32_e32 v5, v5
	v_add_f32_e32 v14, 1.0, v14
	v_add_f32_e32 v15, 1.0, v15
	v_add_f32_e32 v16, 1.0, v4
	v_add_f32_e32 v17, 1.0, v5
	v_rcp_f32_e32 v4, v14
	v_rcp_f32_e32 v5, v15
	v_rcp_f32_e32 v14, v16
	v_rcp_f32_e32 v15, v17
	s_waitcnt vmcnt(0)
	v_lshlrev_b32_e32 v2, 16, v18
	v_and_b32_e32 v3, 0xffff0000, v18
	v_lshlrev_b32_e32 v16, 16, v19
	v_and_b32_e32 v17, 0xffff0000, v19
	v_pk_mul_f32 v[4:5], v[4:5], v[22:23]
	v_pk_mul_f32 v[14:15], v[14:15], v[26:27]
	v_pk_mul_f32 v[2:3], v[4:5], v[2:3]
	v_pk_mul_f32 v[4:5], v[14:15], v[16:17]
	v_cvt_pk_bf16_f32 v2, v2, v3
	v_cvt_pk_bf16_f32 v3, v4, v5
	global_store_dwordx2 v[24:25], v[2:3], off offset:32
	global_load_dwordx4 v[2:5], v[76:77], off
	v_lshl_add_u64 v[14:15], v[20:21], 0, v[80:81]
	global_load_dwordx2 v[14:15], v[14:15], off
	v_or_b32_e32 v16, v0, v59
	v_ashrrev_i32_e32 v17, 31, v16
	v_lshlrev_b32_e32 v18, 16, v44
	v_and_b32_e32 v19, 0xffff0000, v44
	v_lshlrev_b32_e32 v22, 16, v45
	v_and_b32_e32 v23, 0xffff0000, v45
	v_lshlrev_b64 v[16:17], 6, v[16:17]
	v_lshl_add_u64 v[16:17], s[54:55], 0, v[16:17]
	v_lshl_add_u64 v[16:17], v[16:17], 0, v[78:79]
	s_waitcnt vmcnt(1)
	v_add_f32_e32 v0, v10, v2
	v_add_f32_e32 v10, v11, v3
	v_add_f32_e32 v4, v12, v4
	v_add_f32_e32 v5, v13, v5
	v_mul_f32_e32 v0, 0xbfb8aa3b, v0
	v_mul_f32_e32 v10, 0xbfb8aa3b, v10
	v_mul_f32_e32 v4, 0xbfb8aa3b, v4
	v_mul_f32_e32 v5, 0xbfb8aa3b, v5
	v_exp_f32_e32 v0, v0
	v_exp_f32_e32 v10, v10
	v_exp_f32_e32 v4, v4
	v_exp_f32_e32 v5, v5
	v_add_f32_e32 v0, 1.0, v0
	v_add_f32_e32 v10, 1.0, v10
	v_add_f32_e32 v11, 1.0, v4
	v_add_f32_e32 v12, 1.0, v5
	v_rcp_f32_e32 v4, v0
	v_rcp_f32_e32 v5, v10
	v_rcp_f32_e32 v10, v11
	v_rcp_f32_e32 v11, v12
	s_waitcnt vmcnt(0)
	v_lshlrev_b32_e32 v2, 16, v14
	v_and_b32_e32 v3, 0xffff0000, v14
	v_lshlrev_b32_e32 v12, 16, v15
	v_and_b32_e32 v13, 0xffff0000, v15
	v_pk_mul_f32 v[4:5], v[4:5], v[18:19]
	v_pk_mul_f32 v[10:11], v[10:11], v[22:23]
	v_pk_mul_f32 v[2:3], v[4:5], v[2:3]
	v_pk_mul_f32 v[4:5], v[10:11], v[12:13]
	v_cvt_pk_bf16_f32 v2, v2, v3
	v_cvt_pk_bf16_f32 v3, v4, v5
	global_store_dwordx2 v[16:17], v[2:3], off
	global_load_dwordx4 v[2:5], v[72:73], off offset:64
	v_lshl_add_u64 v[10:11], v[20:21], 0, v[74:75]
	global_load_dwordx2 v[10:11], v[10:11], off offset:32
	v_lshlrev_b32_e32 v12, 16, v40
	v_and_b32_e32 v13, 0xffff0000, v40
	v_lshlrev_b32_e32 v14, 16, v41
	v_and_b32_e32 v15, 0xffff0000, v41
	s_waitcnt vmcnt(1)
	v_add_f32_e32 v0, v6, v2
	v_add_f32_e32 v6, v7, v3
	v_add_f32_e32 v4, v8, v4
	v_add_f32_e32 v5, v9, v5
	v_mul_f32_e32 v0, 0xbfb8aa3b, v0
	v_mul_f32_e32 v6, 0xbfb8aa3b, v6
	v_mul_f32_e32 v4, 0xbfb8aa3b, v4
	v_mul_f32_e32 v5, 0xbfb8aa3b, v5
	v_exp_f32_e32 v0, v0
	v_exp_f32_e32 v6, v6
	v_exp_f32_e32 v4, v4
	v_exp_f32_e32 v5, v5
	v_add_f32_e32 v0, 1.0, v0
	v_add_f32_e32 v6, 1.0, v6
	v_add_f32_e32 v7, 1.0, v4
	v_add_f32_e32 v8, 1.0, v5
	v_rcp_f32_e32 v4, v0
	v_rcp_f32_e32 v5, v6
	v_rcp_f32_e32 v6, v7
	v_rcp_f32_e32 v7, v8
	s_waitcnt vmcnt(0)
	v_lshlrev_b32_e32 v2, 16, v10
	v_and_b32_e32 v3, 0xffff0000, v10
	v_lshlrev_b32_e32 v8, 16, v11
	v_and_b32_e32 v9, 0xffff0000, v11
	v_pk_mul_f32 v[4:5], v[4:5], v[12:13]
	v_pk_mul_f32 v[6:7], v[6:7], v[14:15]
	v_pk_mul_f32 v[2:3], v[4:5], v[2:3]
	v_pk_mul_f32 v[4:5], v[6:7], v[8:9]
	v_cvt_pk_bf16_f32 v2, v2, v3
	v_cvt_pk_bf16_f32 v3, v4, v5
	global_store_dwordx2 v[16:17], v[2:3], off offset:32
	s_waitcnt vmcnt(0)
